# mix phase epilogue through a per-wave LDS stage: gate operand read and product written as whole 256-byte rows (dwordx4) instead of 32-byte pieces; same arithmetic
# speedup vs baseline: 1.0085x; 1.0085x over previous
; __device__ __forceinline__ unsigned cvt_pk_bf16(float lo, float hi) { unsigned r; asm("v_cvt_pk_bf16_f32 %0, %1, %2" : "=v"(r) : "v"(lo), "v"(hi)); return r; }
; __device__ __forceinline__ float bf_lo(unsigned w) { return __uint_as_float(w << 16); }
; __device__ __forceinline__ float bf_hi(unsigned w) { return __uint_as_float(w & 0xffff0000u); }
; __device__ __forceinline__ void mix_phase(const Args& a, LAS unsigned char* lds, int G, int wv, size_t aa_out = WS_D) {
;     ...
;         const int q = lane & 15, quad = lane >> 4, row = r0 + 16 * w + q; const float bias = bs[g * 128 + 16 * w + q];
; #pragma unroll
;         for (int mb = 0; mb < 8; ++mb) { u32x2* p = (u32x2*)(GU + (size_t)row * 2048 + c0 + 16 * mb + 4 * quad); const u32x2 uu = *p; p = (u32x2*)((bf16_t*)(a.ws + aa_out) + (size_t)row * 2048 + c0 + 16 * mb + 4 * quad);
;             u32x2 o; o.x = cvt_pk_bf16(bf_lo(uu.x) * (acc[mb][0] + bias), bf_hi(uu.x) * (acc[mb][1] + bias)); o.y = cvt_pk_bf16(bf_lo(uu.y) * (acc[mb][2] + bias), bf_hi(uu.y) * (acc[mb][3] + bias)); *p = o; }
.LBB0_462:
	s_lshl_b32 s68, s97, 7
	v_add_u32_e32 v32, s68, v70
	v_ashrrev_i32_e32 v33, 31, v32
	v_lshl_add_u64 v[32:33], v[32:33], 2, s[74:75]
	global_load_dword v98, v[32:33], off
	s_lshl_b32 s72, s68, 1
	s_mov_b32 s98, 0x4000
	s_mov_b32 s99, 0
	s_mov_b32 s100, s95
	s_mov_b32 s101, 0
	v_mbcnt_lo_u32_b32 v99, -1, 0
	v_mbcnt_hi_u32_b32 v99, -1, v99
	v_and_b32_e32 v100, 15, v99
	v_lshrrev_b32_e32 v101, 4, v99
	v_lshrrev_b32_e32 v102, 4, v70
	v_mul_u32_u24_e32 v102, 0x2100, v102
	v_add_u32_e32 v102, 0x12000, v102
	v_mul_u32_u24_e32 v103, 0x210, v100
	v_lshl_add_u32 v103, v101, 4, v103
	v_add_u32_e32 v103, v102, v103
	v_mul_u32_u24_e32 v107, 0x210, v101
	v_lshl_add_u32 v107, v100, 5, v107
	v_add_u32_e32 v107, v102, v107
	v_sub_u32_e32 v104, v70, v100
	v_add3_u32 v104, v104, v101, s76
	v_mov_b32_e32 v105, 0
	v_lshlrev_b64 v[104:105], 12, v[104:105]
	v_lshl_add_u32 v32, v100, 4, s72
	v_mov_b32_e32 v33, 0
	v_lshl_add_u64 v[104:105], v[104:105], 0, v[32:33]
	v_lshl_add_u64 v[34:35], s[82:83], 0, v[104:105]
	global_load_dwordx4 v[36:39], v[34:35], off
	v_lshl_add_u64 v[34:35], v[34:35], 0, s[98:99]
	global_load_dwordx4 v[66:69], v[34:35], off
	v_lshl_add_u64 v[34:35], v[34:35], 0, s[98:99]
	global_load_dwordx4 v[90:93], v[34:35], off
	v_lshl_add_u64 v[34:35], v[34:35], 0, s[98:99]
	global_load_dwordx4 v[94:97], v[34:35], off
	s_waitcnt vmcnt(4)
	v_add_f32_e32 v0, v98, v0
	v_add_f32_e32 v1, v98, v1
	v_add_f32_e32 v2, v98, v2
	v_add_f32_e32 v3, v98, v3
	v_add_f32_e32 v4, v98, v4
	v_add_f32_e32 v5, v98, v5
	v_add_f32_e32 v6, v98, v6
	v_add_f32_e32 v7, v98, v7
	v_add_f32_e32 v8, v98, v8
	v_add_f32_e32 v9, v98, v9
	v_add_f32_e32 v10, v98, v10
	v_add_f32_e32 v11, v98, v11
	v_add_f32_e32 v12, v98, v12
	v_add_f32_e32 v13, v98, v13
	v_add_f32_e32 v14, v98, v14
	v_add_f32_e32 v15, v98, v15
	v_add_f32_e32 v16, v98, v16
	v_add_f32_e32 v17, v98, v17
	v_add_f32_e32 v18, v98, v18
	v_add_f32_e32 v19, v98, v19
	v_add_f32_e32 v20, v98, v20
	v_add_f32_e32 v21, v98, v21
	v_add_f32_e32 v22, v98, v22
	v_add_f32_e32 v23, v98, v23
	v_add_f32_e32 v24, v98, v24
	v_add_f32_e32 v25, v98, v25
	v_add_f32_e32 v26, v98, v26
	v_add_f32_e32 v27, v98, v27
	v_add_f32_e32 v28, v98, v28
	v_add_f32_e32 v29, v98, v29
	v_add_f32_e32 v30, v98, v30
	v_add_f32_e32 v31, v98, v31
	ds_write_b128 v103, v[28:31]
	ds_write_b128 v103, v[24:27] offset:64
	ds_write_b128 v103, v[20:23] offset:128
	ds_write_b128 v103, v[16:19] offset:192
	ds_write_b128 v103, v[12:15] offset:256
	ds_write_b128 v103, v[8:11] offset:320
	ds_write_b128 v103, v[4:7] offset:384
	ds_write_b128 v103, v[0:3] offset:448
	s_waitcnt lgkmcnt(0)
	ds_read_b128 v[0:3], v107
	ds_read_b128 v[4:7], v107 offset:16
	ds_read_b128 v[8:11], v107 offset:2112
	ds_read_b128 v[12:15], v107 offset:2128
	ds_read_b128 v[16:19], v107 offset:4224
	ds_read_b128 v[20:23], v107 offset:4240
	ds_read_b128 v[24:27], v107 offset:6336
	ds_read_b128 v[28:31], v107 offset:6352
	s_waitcnt vmcnt(0) lgkmcnt(0)
	v_lshlrev_b32_e32 v32, 16, v36
	v_and_b32_e32 v33, 0xffff0000, v36
	v_mul_f32_e32 v0, v0, v32
	v_mul_f32_e32 v1, v1, v33
	v_cvt_pk_bf16_f32 v36, v0, v1
	v_lshlrev_b32_e32 v32, 16, v37
	v_and_b32_e32 v33, 0xffff0000, v37
	v_mul_f32_e32 v2, v2, v32
	v_mul_f32_e32 v3, v3, v33
	v_cvt_pk_bf16_f32 v37, v2, v3
	v_lshlrev_b32_e32 v32, 16, v38
	v_and_b32_e32 v33, 0xffff0000, v38
	v_mul_f32_e32 v4, v4, v32
	v_mul_f32_e32 v5, v5, v33
	v_cvt_pk_bf16_f32 v38, v4, v5
	v_lshlrev_b32_e32 v32, 16, v39
	v_and_b32_e32 v33, 0xffff0000, v39
	v_mul_f32_e32 v6, v6, v32
	v_mul_f32_e32 v7, v7, v33
	v_cvt_pk_bf16_f32 v39, v6, v7
	v_lshlrev_b32_e32 v32, 16, v66
	v_and_b32_e32 v33, 0xffff0000, v66
	v_mul_f32_e32 v8, v8, v32
	v_mul_f32_e32 v9, v9, v33
	v_cvt_pk_bf16_f32 v66, v8, v9
	v_lshlrev_b32_e32 v32, 16, v67
	v_and_b32_e32 v33, 0xffff0000, v67
	v_mul_f32_e32 v10, v10, v32
	v_mul_f32_e32 v11, v11, v33
	v_cvt_pk_bf16_f32 v67, v10, v11
	v_lshlrev_b32_e32 v32, 16, v68
	v_and_b32_e32 v33, 0xffff0000, v68
	v_mul_f32_e32 v12, v12, v32
	v_mul_f32_e32 v13, v13, v33
	v_cvt_pk_bf16_f32 v68, v12, v13
	v_lshlrev_b32_e32 v32, 16, v69
	v_and_b32_e32 v33, 0xffff0000, v69
	v_mul_f32_e32 v14, v14, v32
	v_mul_f32_e32 v15, v15, v33
	v_cvt_pk_bf16_f32 v69, v14, v15
	v_lshlrev_b32_e32 v32, 16, v90
	v_and_b32_e32 v33, 0xffff0000, v90
	v_mul_f32_e32 v16, v16, v32
	v_mul_f32_e32 v17, v17, v33
	v_cvt_pk_bf16_f32 v90, v16, v17
	v_lshlrev_b32_e32 v32, 16, v91
	v_and_b32_e32 v33, 0xffff0000, v91
	v_mul_f32_e32 v18, v18, v32
	v_mul_f32_e32 v19, v19, v33
	v_cvt_pk_bf16_f32 v91, v18, v19
	v_lshlrev_b32_e32 v32, 16, v92
	v_and_b32_e32 v33, 0xffff0000, v92
	v_mul_f32_e32 v20, v20, v32
	v_mul_f32_e32 v21, v21, v33
	v_cvt_pk_bf16_f32 v92, v20, v21
	v_lshlrev_b32_e32 v32, 16, v93
	v_and_b32_e32 v33, 0xffff0000, v93
	v_mul_f32_e32 v22, v22, v32
	v_mul_f32_e32 v23, v23, v33
	v_cvt_pk_bf16_f32 v93, v22, v23
	v_lshlrev_b32_e32 v32, 16, v94
	v_and_b32_e32 v33, 0xffff0000, v94
	v_mul_f32_e32 v24, v24, v32
	v_mul_f32_e32 v25, v25, v33
	v_cvt_pk_bf16_f32 v94, v24, v25
	v_lshlrev_b32_e32 v32, 16, v95
	v_and_b32_e32 v33, 0xffff0000, v95
	v_mul_f32_e32 v26, v26, v32
	v_mul_f32_e32 v27, v27, v33
	v_cvt_pk_bf16_f32 v95, v26, v27
	v_lshlrev_b32_e32 v32, 16, v96
	v_and_b32_e32 v33, 0xffff0000, v96
	v_mul_f32_e32 v28, v28, v32
	v_mul_f32_e32 v29, v29, v33
	v_cvt_pk_bf16_f32 v96, v28, v29
	v_lshlrev_b32_e32 v32, 16, v97
	v_and_b32_e32 v33, 0xffff0000, v97
	v_mul_f32_e32 v30, v30, v32
	v_mul_f32_e32 v31, v31, v33
	v_cvt_pk_bf16_f32 v97, v30, v31
	v_lshl_add_u64 v[34:35], s[78:79], 0, v[104:105]
	v_lshl_add_u64 v[34:35], v[34:35], 0, s[100:101]
	global_store_dwordx4 v[34:35], v[36:39], off
	v_lshl_add_u64 v[34:35], v[34:35], 0, s[98:99]
	global_store_dwordx4 v[34:35], v[66:69], off
	v_lshl_add_u64 v[34:35], v[34:35], 0, s[98:99]
	global_store_dwordx4 v[34:35], v[90:93], off
	v_lshl_add_u64 v[34:35], v[34:35], 0, s[98:99]
	global_store_dwordx4 v[34:35], v[94:97], off
	s_nop 1
	s_add_i32 s96, s96, s89
	s_cmpk_gt_i32 s96, 0x7ff
	s_cbranch_scc1 .LBB0_468
